# grid barrier: the last-arriving XCD leader releases all XCD generation words itself; other leaders wait on their own XCD word (one poll-and-forward hop less)
# speedup vs baseline: 1.0080x; 1.0074x over previous
; __device__ __forceinline__ unsigned xb_ld(unsigned* p)              { return __hip_atomic_load(p, __ATOMIC_RELAXED, __HIP_MEMORY_SCOPE_AGENT); }
; __device__ __forceinline__ unsigned xb_add(unsigned* p, unsigned v) { return __hip_atomic_fetch_add(p, v, __ATOMIC_RELAXED, __HIP_MEMORY_SCOPE_AGENT); }
; #define XB_SPIN(cond, bar) do { unsigned _sp = 0; while (cond) { __builtin_amdgcn_s_sleep(1); \
;     if ((++_sp & 255u) == 0u) { if (xb_ld(&(bar)[XB_TMO])) break; if (_sp > XB_SPIN_CAP) { atomicAdd(&(bar)[XB_TMO], 1u); break; } } } } while (0)
; __device__ __forceinline__ void xcd_barrier(const XcdBarrier& b) {
;     ...
;         const unsigned old = xb_add(&bar[XB_XSUB(b.x)], 1u);
;         const unsigned gen = old / nloc;
;         if (old + 1u == (gen + 1u) * nloc) {
;             __builtin_amdgcn_fence(__ATOMIC_RELEASE, "agent");
;             asm volatile("s_waitcnt vmcnt(0)" ::: "memory");
;             const unsigned og = xb_add(&bar[XB_TOP], 1u);
;             const unsigned tg = og / nx;
;             if (og + 1u == (tg + 1u) * nx) xb_add(&bar[XB_TOPGEN], 1u);
;             else XB_SPIN(xb_ld(&bar[XB_TOPGEN]) == tg, bar);
;             __builtin_amdgcn_fence(__ATOMIC_ACQUIRE, "agent");
;             xb_add(&bar[XB_XGEN(b.x)], 1u);
;             asm volatile("s_waitcnt vmcnt(0)" ::: "memory");
;         } else {
;             XB_SPIN(xb_ld(&bar[XB_XGEN(b.x)]) == gen, bar);
;             __builtin_amdgcn_fence(__ATOMIC_ACQUIRE, "agent");
;             asm volatile("s_waitcnt vmcnt(0)" ::: "memory");
;         }
.LBB0_85:
	s_andn2_saveexec_b64 s[6:7], s[6:7]
	s_cbranch_execz .LBB0_105
	s_mov_b64 s[6:7], exec
	v_readfirstlane_b32 s101, v1
	buffer_wbl2 sc1
	s_waitcnt lgkmcnt(0)
	s_waitcnt vmcnt(0)
	v_mbcnt_lo_u32_b32 v1, s6, 0
	v_mbcnt_hi_u32_b32 v1, s7, v1
	v_cmp_eq_u32_e32 vcc, 0, v1
	s_and_saveexec_b64 s[10:11], vcc
	s_cbranch_execz .LBB0_88
	s_bcnt1_i32_b64 s2, s[6:7]
	v_mov_b32_e32 v2, 0x104000
	v_mov_b32_e32 v3, s2
	global_atomic_add v2, v2, v3, s[34:35] offset:1024 sc0
.LBB0_88:
	s_or_b64 exec, exec, s[10:11]
	v_cvt_f32_u32_e32 v3, v0
	s_waitcnt vmcnt(0)
	v_readfirstlane_b32 s2, v2
	s_add_u32 s10, s34, 0x104500
	s_addc_u32 s11, s35, 0
	v_rcp_iflag_f32_e32 v3, v3
	v_add_u32_e32 v1, s2, v1
	v_add_u32_e32 v4, 1, v1
	s_mov_b64 s[12:13], -1
	v_mul_f32_e32 v2, 0x4f7ffffe, v3
	v_cvt_u32_f32_e32 v2, v2
	v_sub_u32_e32 v3, 0, v0
	v_mul_lo_u32 v3, v3, v2
	v_mul_hi_u32 v3, v2, v3
	v_add_u32_e32 v2, v2, v3
	v_mul_hi_u32 v2, v1, v2
	v_mul_lo_u32 v3, v2, v0
	v_sub_u32_e32 v1, v1, v3
	v_add_u32_e32 v5, 1, v2
	v_cmp_ge_u32_e32 vcc, v1, v0
	v_sub_u32_e32 v3, v1, v0
	s_nop 0
	v_cndmask_b32_e32 v2, v2, v5, vcc
	v_cndmask_b32_e32 v1, v1, v3, vcc
	v_add_u32_e32 v3, 1, v2
	v_cmp_ge_u32_e32 vcc, v1, v0
	s_nop 1
	v_cndmask_b32_e32 v2, v2, v3, vcc
	v_mul_lo_u32 v1, v0, v2
	v_add_u32_e32 v0, v1, v0
	v_cmp_ne_u32_e32 vcc, v4, v0
	v_mov_b64_e32 v[0:1], s[10:11]
	s_and_saveexec_b64 s[6:7], vcc
	s_cbranch_execnz .Lxb_nl1
	s_or_b64 exec, exec, s[6:7]
	v_mov_b32_e32 v2, 1
	v_mov_b32_e32 v3, 0x103400
	global_atomic_add v3, v2, s[34:35]
	global_atomic_add v3, v2, s[34:35] offset:256
	global_atomic_add v3, v2, s[34:35] offset:512
	global_atomic_add v3, v2, s[34:35] offset:768
	global_atomic_add v3, v2, s[34:35] offset:1024
	global_atomic_add v3, v2, s[34:35] offset:1280
	global_atomic_add v3, v2, s[34:35] offset:1536
	global_atomic_add v3, v2, s[34:35] offset:1792
	global_atomic_add v3, v2, s[34:35] offset:2048
	global_atomic_add v3, v2, s[34:35] offset:2304
	global_atomic_add v3, v2, s[34:35] offset:2560
	global_atomic_add v3, v2, s[34:35] offset:2816
	global_atomic_add v3, v2, s[34:35] offset:3072
	global_atomic_add v3, v2, s[34:35] offset:3328
	global_atomic_add v3, v2, s[34:35] offset:3584
	global_atomic_add v3, v2, s[34:35] offset:3840
	s_branch .LBB0_100
.Lxb_nl1:
	s_add_u32 s10, s4, 0x2400
	s_addc_u32 s11, s5, 0
	v_mov_b32_e32 v2, s101
	v_mov_b32_e32 v0, 0
	global_load_dword v1, v0, s[10:11] sc1
	s_mov_b64 s[18:19], 0
	s_waitcnt vmcnt(0)
	v_cmp_eq_u32_e32 vcc, v1, v2
	s_and_saveexec_b64 s[16:17], vcc
	s_cbranch_execz .LBB0_99
	s_add_u32 s12, s34, 0x101200
	s_addc_u32 s13, s35, 0
	s_mov_b32 s2, 1
	s_branch .LBB0_92

; __device__ __forceinline__ unsigned xb_add(unsigned* p, unsigned v) { return __hip_atomic_fetch_add(p, v, __ATOMIC_RELAXED, __HIP_MEMORY_SCOPE_AGENT); }
; __device__ __forceinline__ void xcd_barrier(const XcdBarrier& b) {
;     ...
;             __builtin_amdgcn_fence(__ATOMIC_ACQUIRE, "agent");
;             xb_add(&bar[XB_XGEN(b.x)], 1u);
;             asm volatile("s_waitcnt vmcnt(0)" ::: "memory");
.LBB0_102:
	s_or_b64 exec, exec, s[6:7]
	s_mov_b64 s[6:7], exec
	v_mbcnt_lo_u32_b32 v0, s6, 0
	v_mbcnt_hi_u32_b32 v0, s7, v0
	v_cmp_eq_u32_e32 vcc, 0, v0
	s_waitcnt vmcnt(0)
	buffer_inv sc1
	s_and_saveexec_b64 s[10:11], vcc
	s_branch .LBB0_104
	s_bcnt1_i32_b64 s2, s[6:7]
	v_mov_b32_e32 v0, 0x2000
	v_mov_b32_e32 v1, s2
	global_atomic_add v0, v1, s[4:5] offset:1024

; __device__ __forceinline__ unsigned xb_ld(unsigned* p)              { return __hip_atomic_load(p, __ATOMIC_RELAXED, __HIP_MEMORY_SCOPE_AGENT); }
; __device__ __forceinline__ unsigned xb_add(unsigned* p, unsigned v) { return __hip_atomic_fetch_add(p, v, __ATOMIC_RELAXED, __HIP_MEMORY_SCOPE_AGENT); }
; #define XB_SPIN(cond, bar) do { unsigned _sp = 0; while (cond) { __builtin_amdgcn_s_sleep(1); \
;     if ((++_sp & 255u) == 0u) { if (xb_ld(&(bar)[XB_TMO])) break; if (_sp > XB_SPIN_CAP) { atomicAdd(&(bar)[XB_TMO], 1u); break; } } } } while (0)
; __device__ __forceinline__ void xcd_barrier(const XcdBarrier& b) {
;     ...
;         const unsigned old = xb_add(&bar[XB_XSUB(b.x)], 1u);
;         const unsigned gen = old / nloc;
;         if (old + 1u == (gen + 1u) * nloc) {
;             __builtin_amdgcn_fence(__ATOMIC_RELEASE, "agent");
;             asm volatile("s_waitcnt vmcnt(0)" ::: "memory");
;             const unsigned og = xb_add(&bar[XB_TOP], 1u);
;             const unsigned tg = og / nx;
;             if (og + 1u == (tg + 1u) * nx) xb_add(&bar[XB_TOPGEN], 1u);
;             else XB_SPIN(xb_ld(&bar[XB_TOPGEN]) == tg, bar);
;             __builtin_amdgcn_fence(__ATOMIC_ACQUIRE, "agent");
;             xb_add(&bar[XB_XGEN(b.x)], 1u);
;             asm volatile("s_waitcnt vmcnt(0)" ::: "memory");
;         } else {
;             XB_SPIN(xb_ld(&bar[XB_XGEN(b.x)]) == gen, bar);
;             __builtin_amdgcn_fence(__ATOMIC_ACQUIRE, "agent");
;             asm volatile("s_waitcnt vmcnt(0)" ::: "memory");
;         }
.LBB0_211:
	s_andn2_saveexec_b64 s[6:7], s[6:7]
	s_cbranch_execz .LBB0_231
	s_mov_b64 s[6:7], exec
	v_readfirstlane_b32 s101, v1
	buffer_wbl2 sc1
	s_waitcnt lgkmcnt(0)
	s_waitcnt vmcnt(0)
	v_mbcnt_lo_u32_b32 v1, s6, 0
	v_mbcnt_hi_u32_b32 v1, s7, v1
	v_cmp_eq_u32_e32 vcc, 0, v1
	s_and_saveexec_b64 s[8:9], vcc
	s_cbranch_execz .LBB0_214
	s_bcnt1_i32_b64 s6, s[6:7]
	v_mov_b32_e32 v2, 0x104000
	v_mov_b32_e32 v3, s6
	global_atomic_add v2, v2, v3, s[34:35] offset:1024 sc0
.LBB0_214:
	s_or_b64 exec, exec, s[8:9]
	v_cvt_f32_u32_e32 v3, v0
	s_waitcnt vmcnt(0)
	v_readfirstlane_b32 s6, v2
	s_add_u32 s8, s34, 0x104500
	s_addc_u32 s9, s35, 0
	v_rcp_iflag_f32_e32 v3, v3
	v_add_u32_e32 v1, s6, v1
	v_add_u32_e32 v4, 1, v1
	s_mov_b64 s[10:11], -1
	v_mul_f32_e32 v2, 0x4f7ffffe, v3
	v_cvt_u32_f32_e32 v2, v2
	v_sub_u32_e32 v3, 0, v0
	v_mul_lo_u32 v3, v3, v2
	v_mul_hi_u32 v3, v2, v3
	v_add_u32_e32 v2, v2, v3
	v_mul_hi_u32 v2, v1, v2
	v_mul_lo_u32 v3, v2, v0
	v_sub_u32_e32 v1, v1, v3
	v_add_u32_e32 v5, 1, v2
	v_cmp_ge_u32_e32 vcc, v1, v0
	v_sub_u32_e32 v3, v1, v0
	s_nop 0
	v_cndmask_b32_e32 v2, v2, v5, vcc
	v_cndmask_b32_e32 v1, v1, v3, vcc
	v_add_u32_e32 v3, 1, v2
	v_cmp_ge_u32_e32 vcc, v1, v0
	s_nop 1
	v_cndmask_b32_e32 v2, v2, v3, vcc
	v_mul_lo_u32 v1, v0, v2
	v_add_u32_e32 v0, v1, v0
	v_cmp_ne_u32_e32 vcc, v4, v0
	v_mov_b64_e32 v[0:1], s[8:9]
	s_and_saveexec_b64 s[6:7], vcc
	s_cbranch_execnz .Lxb_nl2
	s_or_b64 exec, exec, s[6:7]
	v_mov_b32_e32 v2, 1
	v_mov_b32_e32 v3, 0x103400
	global_atomic_add v3, v2, s[34:35]
	global_atomic_add v3, v2, s[34:35] offset:256
	global_atomic_add v3, v2, s[34:35] offset:512
	global_atomic_add v3, v2, s[34:35] offset:768
	global_atomic_add v3, v2, s[34:35] offset:1024
	global_atomic_add v3, v2, s[34:35] offset:1280
	global_atomic_add v3, v2, s[34:35] offset:1536
	global_atomic_add v3, v2, s[34:35] offset:1792
	global_atomic_add v3, v2, s[34:35] offset:2048
	global_atomic_add v3, v2, s[34:35] offset:2304
	global_atomic_add v3, v2, s[34:35] offset:2560
	global_atomic_add v3, v2, s[34:35] offset:2816
	global_atomic_add v3, v2, s[34:35] offset:3072
	global_atomic_add v3, v2, s[34:35] offset:3328
	global_atomic_add v3, v2, s[34:35] offset:3584
	global_atomic_add v3, v2, s[34:35] offset:3840
	s_branch .LBB0_226
.Lxb_nl2:
	s_add_u32 s8, s4, 0x2400
	s_addc_u32 s9, s5, 0
	v_mov_b32_e32 v2, s101
	v_mov_b32_e32 v0, 0
	global_load_dword v1, v0, s[8:9] sc1
	s_mov_b64 s[16:17], 0
	s_waitcnt vmcnt(0)
	v_cmp_eq_u32_e32 vcc, v1, v2
	s_and_saveexec_b64 s[12:13], vcc
	s_cbranch_execz .LBB0_225
	s_add_u32 s10, s34, 0x101200
	s_addc_u32 s11, s35, 0
	s_mov_b32 s15, 1
	s_branch .LBB0_218

; __device__ __forceinline__ unsigned xb_add(unsigned* p, unsigned v) { return __hip_atomic_fetch_add(p, v, __ATOMIC_RELAXED, __HIP_MEMORY_SCOPE_AGENT); }
; __device__ __forceinline__ void xcd_barrier(const XcdBarrier& b) {
;     ...
;             __builtin_amdgcn_fence(__ATOMIC_ACQUIRE, "agent");
;             xb_add(&bar[XB_XGEN(b.x)], 1u);
;             asm volatile("s_waitcnt vmcnt(0)" ::: "memory");
.LBB0_228:
	s_or_b64 exec, exec, s[6:7]
	s_mov_b64 s[6:7], exec
	v_mbcnt_lo_u32_b32 v0, s6, 0
	v_mbcnt_hi_u32_b32 v0, s7, v0
	v_cmp_eq_u32_e32 vcc, 0, v0
	s_waitcnt vmcnt(0)
	buffer_inv sc1
	s_and_saveexec_b64 s[8:9], vcc
	s_branch .LBB0_230
	s_bcnt1_i32_b64 s6, s[6:7]
	v_mov_b32_e32 v0, 0x2000
	v_mov_b32_e32 v1, s6
	global_atomic_add v0, v1, s[4:5] offset:1024

; __device__ __forceinline__ unsigned xb_ld(unsigned* p)              { return __hip_atomic_load(p, __ATOMIC_RELAXED, __HIP_MEMORY_SCOPE_AGENT); }
; __device__ __forceinline__ unsigned xb_add(unsigned* p, unsigned v) { return __hip_atomic_fetch_add(p, v, __ATOMIC_RELAXED, __HIP_MEMORY_SCOPE_AGENT); }
; #define XB_SPIN(cond, bar) do { unsigned _sp = 0; while (cond) { __builtin_amdgcn_s_sleep(1); \
;     if ((++_sp & 255u) == 0u) { if (xb_ld(&(bar)[XB_TMO])) break; if (_sp > XB_SPIN_CAP) { atomicAdd(&(bar)[XB_TMO], 1u); break; } } } } while (0)
; __device__ __forceinline__ void xcd_barrier(const XcdBarrier& b) {
;     ...
;         const unsigned old = xb_add(&bar[XB_XSUB(b.x)], 1u);
;         const unsigned gen = old / nloc;
;         if (old + 1u == (gen + 1u) * nloc) {
;             __builtin_amdgcn_fence(__ATOMIC_RELEASE, "agent");
;             asm volatile("s_waitcnt vmcnt(0)" ::: "memory");
;             const unsigned og = xb_add(&bar[XB_TOP], 1u);
;             const unsigned tg = og / nx;
;             if (og + 1u == (tg + 1u) * nx) xb_add(&bar[XB_TOPGEN], 1u);
;             else XB_SPIN(xb_ld(&bar[XB_TOPGEN]) == tg, bar);
;             __builtin_amdgcn_fence(__ATOMIC_ACQUIRE, "agent");
;             xb_add(&bar[XB_XGEN(b.x)], 1u);
;             asm volatile("s_waitcnt vmcnt(0)" ::: "memory");
;         } else {
;             XB_SPIN(xb_ld(&bar[XB_XGEN(b.x)]) == gen, bar);
;             __builtin_amdgcn_fence(__ATOMIC_ACQUIRE, "agent");
;             asm volatile("s_waitcnt vmcnt(0)" ::: "memory");
;         }
.LBB0_431:
	s_andn2_saveexec_b64 s[6:7], s[6:7]
	s_cbranch_execz .LBB0_451
	s_mov_b64 s[6:7], exec
	v_readfirstlane_b32 s101, v1
	buffer_wbl2 sc1
	s_waitcnt lgkmcnt(0)
	s_waitcnt vmcnt(0)
	v_mbcnt_lo_u32_b32 v1, s6, 0
	v_mbcnt_hi_u32_b32 v1, s7, v1
	v_cmp_eq_u32_e32 vcc, 0, v1
	s_and_saveexec_b64 s[10:11], vcc
	s_cbranch_execz .LBB0_434
	s_bcnt1_i32_b64 s6, s[6:7]
	v_mov_b32_e32 v2, 0x104000
	v_mov_b32_e32 v3, s6
	global_atomic_add v2, v2, v3, s[34:35] offset:1024 sc0
.LBB0_434:
	s_or_b64 exec, exec, s[10:11]
	v_cvt_f32_u32_e32 v3, v0
	s_waitcnt vmcnt(0)
	v_readfirstlane_b32 s6, v2
	s_add_u32 s10, s34, 0x104500
	s_addc_u32 s11, s35, 0
	v_rcp_iflag_f32_e32 v3, v3
	v_add_u32_e32 v1, s6, v1
	v_add_u32_e32 v4, 1, v1
	s_mov_b64 s[12:13], -1
	v_mul_f32_e32 v2, 0x4f7ffffe, v3
	v_cvt_u32_f32_e32 v2, v2
	v_sub_u32_e32 v3, 0, v0
	v_mul_lo_u32 v3, v3, v2
	v_mul_hi_u32 v3, v2, v3
	v_add_u32_e32 v2, v2, v3
	v_mul_hi_u32 v2, v1, v2
	v_mul_lo_u32 v3, v2, v0
	v_sub_u32_e32 v1, v1, v3
	v_add_u32_e32 v5, 1, v2
	v_cmp_ge_u32_e32 vcc, v1, v0
	v_sub_u32_e32 v3, v1, v0
	s_nop 0
	v_cndmask_b32_e32 v2, v2, v5, vcc
	v_cndmask_b32_e32 v1, v1, v3, vcc
	v_add_u32_e32 v3, 1, v2
	v_cmp_ge_u32_e32 vcc, v1, v0
	s_nop 1
	v_cndmask_b32_e32 v2, v2, v3, vcc
	v_mul_lo_u32 v1, v0, v2
	v_add_u32_e32 v0, v1, v0
	v_cmp_ne_u32_e32 vcc, v4, v0
	v_mov_b64_e32 v[0:1], s[10:11]
	s_and_saveexec_b64 s[6:7], vcc
	s_cbranch_execnz .Lxb_nl3
	s_or_b64 exec, exec, s[6:7]
	v_mov_b32_e32 v2, 1
	v_mov_b32_e32 v3, 0x103400
	global_atomic_add v3, v2, s[34:35]
	global_atomic_add v3, v2, s[34:35] offset:256
	global_atomic_add v3, v2, s[34:35] offset:512
	global_atomic_add v3, v2, s[34:35] offset:768
	global_atomic_add v3, v2, s[34:35] offset:1024
	global_atomic_add v3, v2, s[34:35] offset:1280
	global_atomic_add v3, v2, s[34:35] offset:1536
	global_atomic_add v3, v2, s[34:35] offset:1792
	global_atomic_add v3, v2, s[34:35] offset:2048
	global_atomic_add v3, v2, s[34:35] offset:2304
	global_atomic_add v3, v2, s[34:35] offset:2560
	global_atomic_add v3, v2, s[34:35] offset:2816
	global_atomic_add v3, v2, s[34:35] offset:3072
	global_atomic_add v3, v2, s[34:35] offset:3328
	global_atomic_add v3, v2, s[34:35] offset:3584
	global_atomic_add v3, v2, s[34:35] offset:3840
	s_branch .LBB0_446
.Lxb_nl3:
	s_add_u32 s10, s4, 0x2400
	s_addc_u32 s11, s5, 0
	v_mov_b32_e32 v2, s101
	v_mov_b32_e32 v0, 0
	global_load_dword v1, v0, s[10:11] sc1
	s_mov_b64 s[18:19], 0
	s_waitcnt vmcnt(0)
	v_cmp_eq_u32_e32 vcc, v1, v2
	s_and_saveexec_b64 s[16:17], vcc
	s_cbranch_execz .LBB0_445
	s_add_u32 s12, s34, 0x101200
	s_addc_u32 s13, s35, 0
	s_mov_b32 s33, 1
	s_branch .LBB0_438

; __device__ __forceinline__ unsigned xb_add(unsigned* p, unsigned v) { return __hip_atomic_fetch_add(p, v, __ATOMIC_RELAXED, __HIP_MEMORY_SCOPE_AGENT); }
; __device__ __forceinline__ void xcd_barrier(const XcdBarrier& b) {
;     ...
;             __builtin_amdgcn_fence(__ATOMIC_ACQUIRE, "agent");
;             xb_add(&bar[XB_XGEN(b.x)], 1u);
;             asm volatile("s_waitcnt vmcnt(0)" ::: "memory");
.LBB0_448:
	s_or_b64 exec, exec, s[6:7]
	s_mov_b64 s[6:7], exec
	v_mbcnt_lo_u32_b32 v0, s6, 0
	v_mbcnt_hi_u32_b32 v0, s7, v0
	v_cmp_eq_u32_e32 vcc, 0, v0
	s_waitcnt vmcnt(0)
	buffer_inv sc1
	s_and_saveexec_b64 s[10:11], vcc
	s_branch .LBB0_450
	s_bcnt1_i32_b64 s6, s[6:7]
	v_mov_b32_e32 v0, 0x2000
	v_mov_b32_e32 v1, s6
	global_atomic_add v0, v1, s[4:5] offset:1024

; __device__ __forceinline__ unsigned xb_ld(unsigned* p)              { return __hip_atomic_load(p, __ATOMIC_RELAXED, __HIP_MEMORY_SCOPE_AGENT); }
; __device__ __forceinline__ unsigned xb_add(unsigned* p, unsigned v) { return __hip_atomic_fetch_add(p, v, __ATOMIC_RELAXED, __HIP_MEMORY_SCOPE_AGENT); }
; #define XB_SPIN(cond, bar) do { unsigned _sp = 0; while (cond) { __builtin_amdgcn_s_sleep(1); \
;     if ((++_sp & 255u) == 0u) { if (xb_ld(&(bar)[XB_TMO])) break; if (_sp > XB_SPIN_CAP) { atomicAdd(&(bar)[XB_TMO], 1u); break; } } } } while (0)
; __device__ __forceinline__ void xcd_barrier(const XcdBarrier& b) {
;     ...
;         const unsigned old = xb_add(&bar[XB_XSUB(b.x)], 1u);
;         const unsigned gen = old / nloc;
;         if (old + 1u == (gen + 1u) * nloc) {
;             __builtin_amdgcn_fence(__ATOMIC_RELEASE, "agent");
;             asm volatile("s_waitcnt vmcnt(0)" ::: "memory");
;             const unsigned og = xb_add(&bar[XB_TOP], 1u);
;             const unsigned tg = og / nx;
;             if (og + 1u == (tg + 1u) * nx) xb_add(&bar[XB_TOPGEN], 1u);
;             else XB_SPIN(xb_ld(&bar[XB_TOPGEN]) == tg, bar);
;             __builtin_amdgcn_fence(__ATOMIC_ACQUIRE, "agent");
;             xb_add(&bar[XB_XGEN(b.x)], 1u);
;             asm volatile("s_waitcnt vmcnt(0)" ::: "memory");
;         } else {
;             XB_SPIN(xb_ld(&bar[XB_XGEN(b.x)]) == gen, bar);
;             __builtin_amdgcn_fence(__ATOMIC_ACQUIRE, "agent");
;             asm volatile("s_waitcnt vmcnt(0)" ::: "memory");
;         }
.LBB0_945:
	s_andn2_saveexec_b64 s[6:7], s[6:7]
	s_cbranch_execz .LBB0_965
	s_mov_b64 s[6:7], exec
	v_readfirstlane_b32 s101, v1
	buffer_wbl2 sc1
	s_waitcnt lgkmcnt(0)
	s_waitcnt vmcnt(0)
	v_mbcnt_lo_u32_b32 v1, s6, 0
	v_mbcnt_hi_u32_b32 v1, s7, v1
	v_cmp_eq_u32_e32 vcc, 0, v1
	s_and_saveexec_b64 s[8:9], vcc
	s_cbranch_execz .LBB0_948
	s_bcnt1_i32_b64 s2, s[6:7]
	v_mov_b32_e32 v2, 0x104000
	v_mov_b32_e32 v3, s2
	global_atomic_add v2, v2, v3, s[34:35] offset:1024 sc0
.LBB0_948:
	s_or_b64 exec, exec, s[8:9]
	v_cvt_f32_u32_e32 v3, v0
	s_waitcnt vmcnt(0)
	v_readfirstlane_b32 s2, v2
	s_add_u32 s8, s34, 0x104500
	s_addc_u32 s9, s35, 0
	v_rcp_iflag_f32_e32 v3, v3
	v_add_u32_e32 v1, s2, v1
	v_add_u32_e32 v4, 1, v1
	s_mov_b64 s[10:11], -1
	v_mul_f32_e32 v2, 0x4f7ffffe, v3
	v_cvt_u32_f32_e32 v2, v2
	v_sub_u32_e32 v3, 0, v0
	v_mul_lo_u32 v3, v3, v2
	v_mul_hi_u32 v3, v2, v3
	v_add_u32_e32 v2, v2, v3
	v_mul_hi_u32 v2, v1, v2
	v_mul_lo_u32 v3, v2, v0
	v_sub_u32_e32 v1, v1, v3
	v_add_u32_e32 v5, 1, v2
	v_cmp_ge_u32_e32 vcc, v1, v0
	v_sub_u32_e32 v3, v1, v0
	s_nop 0
	v_cndmask_b32_e32 v2, v2, v5, vcc
	v_cndmask_b32_e32 v1, v1, v3, vcc
	v_add_u32_e32 v3, 1, v2
	v_cmp_ge_u32_e32 vcc, v1, v0
	s_nop 1
	v_cndmask_b32_e32 v2, v2, v3, vcc
	v_mul_lo_u32 v1, v0, v2
	v_add_u32_e32 v0, v1, v0
	v_cmp_ne_u32_e32 vcc, v4, v0
	v_mov_b64_e32 v[0:1], s[8:9]
	s_and_saveexec_b64 s[6:7], vcc
	s_cbranch_execnz .Lxb_nl6
	s_or_b64 exec, exec, s[6:7]
	v_mov_b32_e32 v2, 1
	v_mov_b32_e32 v3, 0x103400
	global_atomic_add v3, v2, s[34:35]
	global_atomic_add v3, v2, s[34:35] offset:256
	global_atomic_add v3, v2, s[34:35] offset:512
	global_atomic_add v3, v2, s[34:35] offset:768
	global_atomic_add v3, v2, s[34:35] offset:1024
	global_atomic_add v3, v2, s[34:35] offset:1280
	global_atomic_add v3, v2, s[34:35] offset:1536
	global_atomic_add v3, v2, s[34:35] offset:1792
	global_atomic_add v3, v2, s[34:35] offset:2048
	global_atomic_add v3, v2, s[34:35] offset:2304
	global_atomic_add v3, v2, s[34:35] offset:2560
	global_atomic_add v3, v2, s[34:35] offset:2816
	global_atomic_add v3, v2, s[34:35] offset:3072
	global_atomic_add v3, v2, s[34:35] offset:3328
	global_atomic_add v3, v2, s[34:35] offset:3584
	global_atomic_add v3, v2, s[34:35] offset:3840
	s_branch .LBB0_960
.Lxb_nl6:
	s_add_u32 s8, s4, 0x2400
	s_addc_u32 s9, s5, 0
	v_mov_b32_e32 v2, s101
	v_mov_b32_e32 v0, 0
	global_load_dword v1, v0, s[8:9] sc1
	s_mov_b64 s[16:17], 0
	s_waitcnt vmcnt(0)
	v_cmp_eq_u32_e32 vcc, v1, v2
	s_and_saveexec_b64 s[12:13], vcc
	s_cbranch_execz .LBB0_959
	s_add_u32 s10, s34, 0x101200
	s_addc_u32 s11, s35, 0
	s_mov_b32 s2, 1
	s_branch .LBB0_952

; __device__ __forceinline__ unsigned xb_add(unsigned* p, unsigned v) { return __hip_atomic_fetch_add(p, v, __ATOMIC_RELAXED, __HIP_MEMORY_SCOPE_AGENT); }
; __device__ __forceinline__ void xcd_barrier(const XcdBarrier& b) {
;     ...
;             __builtin_amdgcn_fence(__ATOMIC_ACQUIRE, "agent");
;             xb_add(&bar[XB_XGEN(b.x)], 1u);
;             asm volatile("s_waitcnt vmcnt(0)" ::: "memory");
.LBB0_962:
	s_or_b64 exec, exec, s[6:7]
	s_mov_b64 s[6:7], exec
	v_mbcnt_lo_u32_b32 v0, s6, 0
	v_mbcnt_hi_u32_b32 v0, s7, v0
	v_cmp_eq_u32_e32 vcc, 0, v0
	s_waitcnt vmcnt(0)
	buffer_inv sc1
	s_and_saveexec_b64 s[8:9], vcc
	s_branch .LBB0_964
	s_bcnt1_i32_b64 s2, s[6:7]
	v_mov_b32_e32 v0, 0x2000
	v_mov_b32_e32 v1, s2
	global_atomic_add v0, v1, s[4:5] offset:1024

; __device__ __forceinline__ unsigned xb_ld(unsigned* p)              { return __hip_atomic_load(p, __ATOMIC_RELAXED, __HIP_MEMORY_SCOPE_AGENT); }
; #define XB_SPIN(cond, bar) do { unsigned _sp = 0; while (cond) { __builtin_amdgcn_s_sleep(1); \
;     if ((++_sp & 255u) == 0u) { if (xb_ld(&(bar)[XB_TMO])) break; if (_sp > XB_SPIN_CAP) { atomicAdd(&(bar)[XB_TMO], 1u); break; } } } } while (0)
; __device__ __forceinline__ void xcd_barrier(const XcdBarrier& b) {
;     ...
;         } else {
;             XB_SPIN(xb_ld(&bar[XB_XGEN(b.x)]) == gen, bar);
;             __builtin_amdgcn_fence(__ATOMIC_ACQUIRE, "agent");
.Lxb_nl9:
	s_add_u32 s8, s4, 0x2400
	s_addc_u32 s9, s5, 0
	v_mov_b32_e32 v2, s101
	v_mov_b32_e32 v0, 0
	global_load_dword v1, v0, s[8:9] sc1
	s_mov_b64 s[14:15], 0
	s_waitcnt vmcnt(0)
	v_cmp_eq_u32_e32 vcc, v1, v2
	s_and_saveexec_b64 s[12:13], vcc
	s_cbranch_execz .LBB0_1775
	s_add_u32 s10, s34, 0x101200
	s_addc_u32 s11, s35, 0
	s_mov_b32 s24, 1
	s_branch .LBB0_1768

; __device__ __forceinline__ unsigned xb_ld(unsigned* p)              { return __hip_atomic_load(p, __ATOMIC_RELAXED, __HIP_MEMORY_SCOPE_AGENT); }
; #define XB_SPIN(cond, bar) do { unsigned _sp = 0; while (cond) { __builtin_amdgcn_s_sleep(1); \
;     if ((++_sp & 255u) == 0u) { if (xb_ld(&(bar)[XB_TMO])) break; if (_sp > XB_SPIN_CAP) { atomicAdd(&(bar)[XB_TMO], 1u); break; } } } } while (0)
; __device__ __forceinline__ void xcd_barrier(const XcdBarrier& b) {
;     ...
;         } else {
;             XB_SPIN(xb_ld(&bar[XB_XGEN(b.x)]) == gen, bar);
;             __builtin_amdgcn_fence(__ATOMIC_ACQUIRE, "agent");
.Lxb_nl10:
	s_add_u32 s8, s4, 0x2400
	s_addc_u32 s9, s5, 0
	v_mov_b32_e32 v2, s101
	v_mov_b32_e32 v0, 0
	global_load_dword v1, v0, s[8:9] sc1
	s_mov_b64 s[14:15], 0
	s_waitcnt vmcnt(0)
	v_cmp_eq_u32_e32 vcc, v1, v2
	s_and_saveexec_b64 s[12:13], vcc
	s_cbranch_execz .LBB0_2034
	s_add_u32 s10, s34, 0x101200
	s_addc_u32 s11, s35, 0
	s_mov_b32 s2, 1
	s_branch .LBB0_2027

; __device__ __forceinline__ unsigned xb_ld(unsigned* p)              { return __hip_atomic_load(p, __ATOMIC_RELAXED, __HIP_MEMORY_SCOPE_AGENT); }
; #define XB_SPIN(cond, bar) do { unsigned _sp = 0; while (cond) { __builtin_amdgcn_s_sleep(1); \
;     if ((++_sp & 255u) == 0u) { if (xb_ld(&(bar)[XB_TMO])) break; if (_sp > XB_SPIN_CAP) { atomicAdd(&(bar)[XB_TMO], 1u); break; } } } } while (0)
; __device__ __forceinline__ void xcd_barrier(const XcdBarrier& b) {
;     ...
;         } else {
;             XB_SPIN(xb_ld(&bar[XB_XGEN(b.x)]) == gen, bar);
;             __builtin_amdgcn_fence(__ATOMIC_ACQUIRE, "agent");
.Lxb_nl12:
	s_add_u32 s10, s4, 0x2400
	s_addc_u32 s11, s5, 0
	v_mov_b32_e32 v2, s101
	v_mov_b32_e32 v0, 0
	global_load_dword v1, v0, s[10:11] sc1
	s_mov_b64 s[16:17], 0
	s_waitcnt vmcnt(0)
	v_cmp_eq_u32_e32 vcc, v1, v2
	s_and_saveexec_b64 s[14:15], vcc
	s_cbranch_execz .LBB0_2254
	s_add_u32 s12, s34, 0x101200
	s_addc_u32 s13, s35, 0
	s_mov_b32 s2, 1
	s_branch .LBB0_2247

; __device__ __forceinline__ unsigned xb_ld(unsigned* p)              { return __hip_atomic_load(p, __ATOMIC_RELAXED, __HIP_MEMORY_SCOPE_AGENT); }
; __device__ __forceinline__ unsigned xb_add(unsigned* p, unsigned v) { return __hip_atomic_fetch_add(p, v, __ATOMIC_RELAXED, __HIP_MEMORY_SCOPE_AGENT); }
; #define XB_SPIN(cond, bar) do { unsigned _sp = 0; while (cond) { __builtin_amdgcn_s_sleep(1); \
;     if ((++_sp & 255u) == 0u) { if (xb_ld(&(bar)[XB_TMO])) break; if (_sp > XB_SPIN_CAP) { atomicAdd(&(bar)[XB_TMO], 1u); break; } } } } while (0)
; __device__ __forceinline__ void xcd_barrier(const XcdBarrier& b) {
;     ...
;         const unsigned old = xb_add(&bar[XB_XSUB(b.x)], 1u);
;         const unsigned gen = old / nloc;
;         if (old + 1u == (gen + 1u) * nloc) {
;             __builtin_amdgcn_fence(__ATOMIC_RELEASE, "agent");
;             asm volatile("s_waitcnt vmcnt(0)" ::: "memory");
;             const unsigned og = xb_add(&bar[XB_TOP], 1u);
;             const unsigned tg = og / nx;
;             if (og + 1u == (tg + 1u) * nx) xb_add(&bar[XB_TOPGEN], 1u);
;             else XB_SPIN(xb_ld(&bar[XB_TOPGEN]) == tg, bar);
;             __builtin_amdgcn_fence(__ATOMIC_ACQUIRE, "agent");
;             xb_add(&bar[XB_XGEN(b.x)], 1u);
;             asm volatile("s_waitcnt vmcnt(0)" ::: "memory");
;         } else {
;             XB_SPIN(xb_ld(&bar[XB_XGEN(b.x)]) == gen, bar);
;             __builtin_amdgcn_fence(__ATOMIC_ACQUIRE, "agent");
;             asm volatile("s_waitcnt vmcnt(0)" ::: "memory");
;         }
.LBB0_2546:
	s_andn2_saveexec_b64 s[4:5], s[4:5]
	s_cbranch_execz .LBB0_2566
	s_mov_b64 s[4:5], exec
	v_readfirstlane_b32 s101, v1
	buffer_wbl2 sc1
	s_waitcnt lgkmcnt(0)
	s_waitcnt vmcnt(0)
	v_mbcnt_lo_u32_b32 v1, s4, 0
	v_mbcnt_hi_u32_b32 v1, s5, v1
	v_cmp_eq_u32_e32 vcc, 0, v1
	s_and_saveexec_b64 s[6:7], vcc
	s_cbranch_execz .LBB0_2549
	s_bcnt1_i32_b64 s4, s[4:5]
	v_mov_b32_e32 v2, 0x104000
	v_mov_b32_e32 v3, s4
	global_atomic_add v2, v2, v3, s[34:35] offset:1024 sc0
.LBB0_2549:
	s_or_b64 exec, exec, s[6:7]
	v_cvt_f32_u32_e32 v3, v0
	s_waitcnt vmcnt(0)
	v_readfirstlane_b32 s4, v2
	s_add_u32 s6, s34, 0x104500
	s_addc_u32 s7, s35, 0
	v_rcp_iflag_f32_e32 v3, v3
	v_add_u32_e32 v1, s4, v1
	v_add_u32_e32 v4, 1, v1
	s_mov_b64 s[8:9], -1
	v_mul_f32_e32 v2, 0x4f7ffffe, v3
	v_cvt_u32_f32_e32 v2, v2
	v_sub_u32_e32 v3, 0, v0
	v_mul_lo_u32 v3, v3, v2
	v_mul_hi_u32 v3, v2, v3
	v_add_u32_e32 v2, v2, v3
	v_mul_hi_u32 v2, v1, v2
	v_mul_lo_u32 v3, v2, v0
	v_sub_u32_e32 v1, v1, v3
	v_add_u32_e32 v5, 1, v2
	v_cmp_ge_u32_e32 vcc, v1, v0
	v_sub_u32_e32 v3, v1, v0
	s_nop 0
	v_cndmask_b32_e32 v2, v2, v5, vcc
	v_cndmask_b32_e32 v1, v1, v3, vcc
	v_add_u32_e32 v3, 1, v2
	v_cmp_ge_u32_e32 vcc, v1, v0
	s_nop 1
	v_cndmask_b32_e32 v2, v2, v3, vcc
	v_mul_lo_u32 v1, v0, v2
	v_add_u32_e32 v0, v1, v0
	v_cmp_ne_u32_e32 vcc, v4, v0
	v_mov_b64_e32 v[0:1], s[6:7]
	s_and_saveexec_b64 s[4:5], vcc
	s_cbranch_execnz .Lxb_nl15
	s_or_b64 exec, exec, s[4:5]
	v_mov_b32_e32 v2, 1
	v_mov_b32_e32 v3, 0x103400
	global_atomic_add v3, v2, s[34:35]
	global_atomic_add v3, v2, s[34:35] offset:256
	global_atomic_add v3, v2, s[34:35] offset:512
	global_atomic_add v3, v2, s[34:35] offset:768
	global_atomic_add v3, v2, s[34:35] offset:1024
	global_atomic_add v3, v2, s[34:35] offset:1280
	global_atomic_add v3, v2, s[34:35] offset:1536
	global_atomic_add v3, v2, s[34:35] offset:1792
	global_atomic_add v3, v2, s[34:35] offset:2048
	global_atomic_add v3, v2, s[34:35] offset:2304
	global_atomic_add v3, v2, s[34:35] offset:2560
	global_atomic_add v3, v2, s[34:35] offset:2816
	global_atomic_add v3, v2, s[34:35] offset:3072
	global_atomic_add v3, v2, s[34:35] offset:3328
	global_atomic_add v3, v2, s[34:35] offset:3584
	global_atomic_add v3, v2, s[34:35] offset:3840
	s_branch .LBB0_2561
.Lxb_nl15:
	s_add_u32 s6, s2, 0x2400
	s_addc_u32 s7, s3, 0
	v_mov_b32_e32 v2, s101
	v_mov_b32_e32 v0, 0
	global_load_dword v1, v0, s[6:7] sc1
	s_mov_b64 s[12:13], 0
	s_waitcnt vmcnt(0)
	v_cmp_eq_u32_e32 vcc, v1, v2
	s_and_saveexec_b64 s[10:11], vcc
	s_cbranch_execz .LBB0_2560
	s_add_u32 s8, s34, 0x101200
	s_addc_u32 s9, s35, 0
	s_mov_b32 s22, 1
	s_branch .LBB0_2553

; __device__ __forceinline__ unsigned xb_add(unsigned* p, unsigned v) { return __hip_atomic_fetch_add(p, v, __ATOMIC_RELAXED, __HIP_MEMORY_SCOPE_AGENT); }
; __device__ __forceinline__ void xcd_barrier(const XcdBarrier& b) {
;     ...
;             __builtin_amdgcn_fence(__ATOMIC_ACQUIRE, "agent");
;             xb_add(&bar[XB_XGEN(b.x)], 1u);
;             asm volatile("s_waitcnt vmcnt(0)" ::: "memory");
.LBB0_2563:
	s_or_b64 exec, exec, s[4:5]
	s_mov_b64 s[4:5], exec
	v_mbcnt_lo_u32_b32 v0, s4, 0
	v_mbcnt_hi_u32_b32 v0, s5, v0
	v_cmp_eq_u32_e32 vcc, 0, v0
	s_waitcnt vmcnt(0)
	buffer_inv sc1
	s_and_saveexec_b64 s[6:7], vcc
	s_branch .LBB0_2565
	s_bcnt1_i32_b64 s4, s[4:5]
	v_mov_b32_e32 v0, 0x2000
	v_mov_b32_e32 v1, s4
	global_atomic_add v0, v1, s[2:3] offset:1024
